# band items dealt to the eight XCD queues in 96-item blocks per class so every queue carries the same share of the gated (heavier) window-mixer items
# baseline (speedup 1.0000x reference)
; DI void band_item(const Params& P, char* lds_blk, int layer, int bp) {
;     ...
;     const int type = bp / 768, rem = bp % 768; const int bl = rem / 384, head = 2 * ((rem % 384) / 64) + half, blk = rem % 64;
;     const int dil = type <= 1 ? 1 : (type == 2 ? 4 : 16);
;     const int nper = 64 / dil; const int residue = blk / nper, nb = blk % nper;
; DI void phase_att(const Params& P, char* lds, int hb, int layer) {
;     ...
;             if (qi >= NQ) break;
;             if (qi < 64) diff_item(P, lds, layer, qx, 63 - qi, tab_head);
;             else band_item(P, lds, layer, qx * 384 + (qi - 64));
.LBB0_201:
	s_or_b64 exec, exec, s[0:1]
	v_mov_b32_e32 v0, s53
	s_waitcnt lgkmcnt(0)
	s_barrier
	ds_read_b32 v0, v0
	s_movk_i32 s0, 0x1bf
	s_waitcnt lgkmcnt(0)
	s_barrier
	v_cmp_lt_i32_e64 s[38:39], s0, v0
	v_readfirstlane_b32 s25, v0
	s_and_b64 vcc, exec, s[38:39]
	s_cbranch_vccnz .LBB0_198
	s_cmp_gt_i32 s25, 63
	s_mov_b64 s[0:1], -1
	s_cbranch_scc0 .LBB0_243
	s_add_i32 s63, s25, -64
	s_mul_i32 s0, s63, 0x2ab
	s_lshr_b32 s0, s0, 16
	s_mul_i32 s0, s0, 0x2a0
	s_add_i32 s63, s63, s0
	s_add_i32 s0, s26, s33
	s_and_b32 s0, s0, 7
	s_mul_i32 s0, s0, 0x60
	s_add_i32 s63, s63, s0
	s_and_b32 s0, s63, 0xffff
	s_mul_i32 s0, s0, 0xaaab
	s_lshr_b32 s50, s0, 25
	s_mul_i32 s0, s50, 0x300
	s_sub_i32 s0, s63, s0
	s_and_b32 s16, s0, 0xffff
	s_add_i32 s0, s16, 0x80
	s_cmpk_lt_u32 s16, 0x180
	s_cselect_b32 s0, s16, s0
	s_lshr_b32 s0, s0, 5
	v_mov_b32_e32 v10, v174
	s_and_b32 s0, s0, 14
	s_cmpk_lt_u32 s63, 0x300
	v_ashrrev_i32_e32 v0, 8, v10
	v_add_u32_e32 v108, s0, v0
	s_cselect_b64 s[0:1], -1, 0
	s_cmpk_gt_u32 s63, 0x2ff
	s_cselect_b64 s[40:41], -1, 0
	v_lshlrev_b32_e32 v106, 6, v108
	s_mov_b64 s[22:23], -1
	s_and_b64 vcc, exec, s[40:41]
	s_cbranch_vccz .LBB0_205
	v_add_u32_e32 v2, 0x480, v106
	v_add_u32_e32 v4, 0x780, v106
	v_add_u32_e32 v6, 0xa80, v106
	s_mov_b64 s[22:23], 0
